# v54 + P7 chunk loop: Horner VALU of tiles 0/1 interleaved with the last 8 MFMAs of tiles 2/3 (reorder only, distances re-padded)
# baseline (speedup 1.0000x reference)
; template <int DIR>
; __device__ __forceinline__ void s5_local_dir(const bf16_t* UZ, unsigned char* ws, int gw, int NGW, int lane) {
;     ...
; #pragma unroll
;         for (int t = 0; t < 4; ++t) {
;             f32x4 cr = {0.f, 0.f, 0.f, 0.f}, ci = {0.f, 0.f, 0.f, 0.f};
; #pragma unroll
;             for (int m = 0; m < 4; ++m) {
;                 cr = __builtin_amdgcn_mfma_f32_16x16x16bf16_1k(Uf[m], Bre[m][t], cr, 0, 0, 0);
;                 ci = __builtin_amdgcn_mfma_f32_16x16x16bf16_1k(Uf[m], Bim[m][t], ci, 0, 0, 0);
;             }
;             f32x2 s2 = {DIR ? cr[3] : cr[0], DIR ? ci[3] : ci[0]};
; #pragma unroll
;             for (int ii = 1; ii < 4; ++ii) { const int i = DIR ? 3 - ii : ii;
;                 s2 = cmac(s2, (f32x2){a1r[t], a1r[t]}, (f32x2){-a1i[t], a1i[t]}, (f32x2){cr[i], ci[i]}); }
;             s2 = cmac(s2, (f32x2){wr_[t], wr_[t]}, (f32x2){-wi_[t], wi_[t]}, (f32x2){0.f, 0.f});
;             float sr = s2.x, si = s2.y;
;             sr += __shfl_xor(sr, 16); si += __shfl_xor(si, 16); sr += __shfl_xor(sr, 32); si += __shfl_xor(si, 32);
;             if (fq == 0) { e[16 * t + fr] = Rr[t]; e[64 + 16 * t + fr] = Ri[t]; }
;             const float nr = fmaf(a64r[t], Rr[t], fmaf(-a64i[t], Ri[t], sr)), ni = fmaf(a64r[t], Ri[t], fmaf(a64i[t], Rr[t], si)); Rr[t] = nr; Ri[t] = ni;
;         }
.LBB0_652:
	global_store_dword v[116:117], v240, off offset:-256
	global_store_dword v[116:117], v241, off
	s_waitcnt vmcnt(9)
	v_mfma_f32_16x16x16_bf16 v[140:143], v[110:111], v[26:27], 0
	v_mfma_f32_16x16x16_bf16 v[144:147], v[110:111], v[28:29], 0
	s_waitcnt vmcnt(8)
	v_mfma_f32_16x16x16_bf16 v[140:143], v[112:113], v[30:31], v[140:143]
	v_mfma_f32_16x16x16_bf16 v[144:147], v[112:113], v[32:33], v[144:147]
	s_waitcnt vmcnt(7)
	v_mfma_f32_16x16x16_bf16 v[140:143], v[114:115], v[34:35], v[140:143]
	v_mfma_f32_16x16x16_bf16 v[144:147], v[114:115], v[36:37], v[144:147]
	s_waitcnt vmcnt(6)
	v_mfma_f32_16x16x16_bf16 v[140:143], v[108:109], v[38:39], v[140:143]
	v_mfma_f32_16x16x16_bf16 v[144:147], v[108:109], v[40:41], v[144:147]
	v_mfma_f32_16x16x16_bf16 v[196:199], v[110:111], v[48:49], 0
	v_mfma_f32_16x16x16_bf16 v[200:203], v[110:111], v[50:51], 0
	v_mfma_f32_16x16x16_bf16 v[196:199], v[112:113], v[52:53], v[196:199]
	v_mfma_f32_16x16x16_bf16 v[200:203], v[112:113], v[54:55], v[200:203]
	v_mfma_f32_16x16x16_bf16 v[196:199], v[114:115], v[56:57], v[196:199]
	v_mfma_f32_16x16x16_bf16 v[200:203], v[114:115], v[58:59], v[200:203]
	v_mfma_f32_16x16x16_bf16 v[196:199], v[108:109], v[60:61], v[196:199]
	v_mfma_f32_16x16x16_bf16 v[200:203], v[108:109], v[62:63], v[200:203]
	v_mfma_f32_16x16x16_bf16 v[208:211], v[110:111], v[70:71], 0
	v_mfma_f32_16x16x16_bf16 v[212:215], v[110:111], v[72:73], 0
	v_mfma_f32_16x16x16_bf16 v[208:211], v[112:113], v[74:75], v[208:211]
	v_mfma_f32_16x16x16_bf16 v[212:215], v[112:113], v[76:77], v[212:215]
	v_mfma_f32_16x16x16_bf16 v[228:231], v[110:111], v[92:93], 0
	v_mfma_f32_16x16x16_bf16 v[232:235], v[110:111], v[94:95], 0
	v_mfma_f32_16x16x16_bf16 v[228:231], v[112:113], v[96:97], v[228:231]
	v_mfma_f32_16x16x16_bf16 v[186:189], v[112:113], v[98:99], v[232:235]
	v_mov_b32_e32 v148, v143
	v_mov_b32_e32 v204, v199
	v_mov_b32_e32 v149, v147
	v_mov_b32_e32 v205, v203
	v_mfma_f32_16x16x16_bf16 v[208:211], v[114:115], v[78:79], v[208:211]
	v_mov_b32_e32 v150, v142
	v_mov_b32_e32 v206, v198
	v_mov_b32_e32 v151, v146
	v_mov_b32_e32 v207, v202
	v_mfma_f32_16x16x16_bf16 v[228:231], v[114:115], v[100:101], v[228:231]
	v_pk_fma_f32 v[148:149], v[20:21], v[148:149], v[150:151]
	v_pk_fma_f32 v[204:205], v[42:43], v[204:205], v[206:207]
	v_mov_b32_e32 v142, v147
	v_mov_b32_e32 v198, v203
	v_mfma_f32_16x16x16_bf16 v[212:215], v[114:115], v[80:81], v[212:215]
	v_pk_fma_f32 v[142:143], v[0:1], v[142:143], v[148:149]
	v_pk_fma_f32 v[198:199], v[4:5], v[198:199], v[204:205]
	v_mov_b32_e32 v146, v141
	v_mov_b32_e32 v202, v197
	v_mfma_f32_16x16x16_bf16 v[186:189], v[114:115], v[102:103], v[186:189]
	v_mov_b32_e32 v147, v145
	v_mov_b32_e32 v203, v201
	v_pk_fma_f32 v[146:147], v[20:21], v[142:143], v[146:147]
	v_pk_fma_f32 v[202:203], v[42:43], v[198:199], v[202:203]
	v_mfma_f32_16x16x16_bf16 v[208:211], v[108:109], v[82:83], v[208:211]
	v_mov_b32_e32 v141, v144
	v_mov_b32_e32 v197, v200
	v_pk_fma_f32 v[142:143], v[0:1], v[142:143], v[146:147] op_sel:[0,1,0] op_sel_hi:[1,0,1]
	v_pk_fma_f32 v[198:199], v[4:5], v[198:199], v[202:203] op_sel:[0,1,0] op_sel_hi:[1,0,1]
	v_mfma_f32_16x16x16_bf16 v[228:231], v[108:109], v[104:105], v[228:231]
	s_nop 0
	s_nop 0
	v_pk_fma_f32 v[140:141], v[20:21], v[142:143], v[140:141]
	v_pk_fma_f32 v[196:197], v[42:43], v[198:199], v[196:197]
	v_mfma_f32_16x16x16_bf16 v[212:215], v[108:109], v[84:85], v[212:215]
	s_nop 0
	s_nop 0
	v_pk_fma_f32 v[140:141], v[0:1], v[142:143], v[140:141] op_sel:[0,1,0] op_sel_hi:[1,0,1]
	v_pk_fma_f32 v[196:197], v[4:5], v[198:199], v[196:197] op_sel:[0,1,0] op_sel_hi:[1,0,1]
	v_mfma_f32_16x16x16_bf16 v[184:187], v[108:109], v[106:107], v[186:189]
	s_nop 0
	s_nop 0
	v_pk_fma_f32 v[142:143], v[22:23], v[140:141], 0 op_sel_hi:[1,1,0]
	v_pk_fma_f32 v[198:199], v[44:45], v[196:197], 0 op_sel_hi:[1,1,0]
	s_nop 0
	s_nop 0
	v_pk_fma_f32 v[140:141], v[24:25], v[140:141], v[142:143] op_sel:[0,1,0] op_sel_hi:[1,0,1]
	v_pk_fma_f32 v[196:197], v[46:47], v[196:197], v[198:199] op_sel:[0,1,0] op_sel_hi:[1,0,1]
	v_mov_b32_e32 v216, v211
	v_mov_b32_e32 v190, v231
	v_mov_b32_e32 v217, v215
	v_mov_b32_e32 v191, v187
	v_mov_b32_e32 v218, v210
	v_mov_b32_e32 v188, v230
	v_mov_b32_e32 v219, v214
	v_mov_b32_e32 v189, v186
	v_pk_fma_f32 v[216:217], v[64:65], v[216:217], v[218:219]
	v_pk_fma_f32 v[188:189], v[86:87], v[190:191], v[188:189]
	v_mov_b32_e32 v210, v215
	v_mov_b32_e32 v230, v187
	v_pk_fma_f32 v[210:211], v[8:9], v[210:211], v[216:217]
	v_pk_fma_f32 v[186:187], v[12:13], v[230:231], v[188:189]
	v_mov_b32_e32 v214, v209
	v_mov_b32_e32 v188, v229
	v_mov_b32_e32 v215, v213
	v_mov_b32_e32 v189, v185
	v_pk_fma_f32 v[214:215], v[64:65], v[210:211], v[214:215]
	v_pk_fma_f32 v[188:189], v[86:87], v[186:187], v[188:189]
	v_mov_b32_e32 v209, v212
	v_mov_b32_e32 v229, v184
	v_pk_fma_f32 v[210:211], v[8:9], v[210:211], v[214:215] op_sel:[0,1,0] op_sel_hi:[1,0,1]
	v_pk_fma_f32 v[186:187], v[12:13], v[186:187], v[188:189] op_sel:[0,1,0] op_sel_hi:[1,0,1]
	s_nop 0
	s_nop 0
	v_pk_fma_f32 v[208:209], v[64:65], v[210:211], v[208:209]
	v_pk_fma_f32 v[184:185], v[86:87], v[186:187], v[228:229]
	s_nop 0
	s_nop 0
	v_pk_fma_f32 v[208:209], v[8:9], v[210:211], v[208:209] op_sel:[0,1,0] op_sel_hi:[1,0,1]
	v_pk_fma_f32 v[184:185], v[12:13], v[186:187], v[184:185] op_sel:[0,1,0] op_sel_hi:[1,0,1]
	s_nop 0
	s_nop 0
	v_pk_fma_f32 v[210:211], v[66:67], v[208:209], 0 op_sel_hi:[1,1,0]
	v_pk_fma_f32 v[186:187], v[88:89], v[184:185], 0 op_sel_hi:[1,1,0]
	s_nop 0
	s_nop 0
	v_pk_fma_f32 v[208:209], v[68:69], v[208:209], v[210:211] op_sel:[0,1,0] op_sel_hi:[1,0,1]
	v_pk_fma_f32 v[184:185], v[90:91], v[184:185], v[186:187] op_sel:[0,1,0] op_sel_hi:[1,0,1]
	s_nop 1
	v_permlane32_swap_b32_e32 v140, v208
	v_permlane32_swap_b32_e32 v141, v209
	v_permlane32_swap_b32_e32 v196, v184
	v_permlane32_swap_b32_e32 v197, v185
	v_add_f32_e32 v140, v140, v208
	v_add_f32_e32 v196, v196, v184
	v_add_f32_e32 v141, v141, v209
	v_add_f32_e32 v197, v197, v185
	s_nop 0
	v_permlane16_swap_b32_e32 v140, v196
	v_permlane16_swap_b32_e32 v141, v197
	v_add_f32_e32 v140, v140, v196
	v_add_f32_e32 v141, v141, v197
	v_fma_f32 v244, -v243, v241, v140
	v_fma_f32 v245, v243, v240, v141
	v_fma_f32 v240, v242, v240, v244
	v_fma_f32 v241, v242, v241, v245
	v_lshl_add_u64 v[116:117], v[116:117], 0, s[2:3]
	v_subrev_u32_e32 v16, 64, v16
	s_and_b64 vcc, exec, s[36:37]
	s_cbranch_vccnz .LBB0_684
	s_mov_b32 s38, s49
	s_waitcnt vmcnt(3)
	v_mov_b32_e32 v110, v118
	v_mov_b32_e32 v111, v119
	s_waitcnt vmcnt(2)
	v_mov_b32_e32 v112, v120
	v_mov_b32_e32 v113, v121
	s_waitcnt vmcnt(1)
	v_mov_b32_e32 v114, v122
	v_mov_b32_e32 v115, v123
	s_waitcnt vmcnt(0)
	v_mov_b32_e32 v108, v124
	v_mov_b32_e32 v109, v125
	s_branch .LBB0_649

; template <int DIR>
; __device__ __forceinline__ void s5_local_dir(const bf16_t* UZ, unsigned char* ws, int gw, int NGW, int lane) {
;     ...
; #pragma unroll
;         for (int t = 0; t < 4; ++t) {
;             f32x4 cr = {0.f, 0.f, 0.f, 0.f}, ci = {0.f, 0.f, 0.f, 0.f};
; #pragma unroll
;             for (int m = 0; m < 4; ++m) {
;                 cr = __builtin_amdgcn_mfma_f32_16x16x16bf16_1k(Uf[m], Bre[m][t], cr, 0, 0, 0);
;                 ci = __builtin_amdgcn_mfma_f32_16x16x16bf16_1k(Uf[m], Bim[m][t], ci, 0, 0, 0);
;             }
;             f32x2 s2 = {DIR ? cr[3] : cr[0], DIR ? ci[3] : ci[0]};
; #pragma unroll
;             for (int ii = 1; ii < 4; ++ii) { const int i = DIR ? 3 - ii : ii;
;                 s2 = cmac(s2, (f32x2){a1r[t], a1r[t]}, (f32x2){-a1i[t], a1i[t]}, (f32x2){cr[i], ci[i]}); }
;             s2 = cmac(s2, (f32x2){wr_[t], wr_[t]}, (f32x2){-wi_[t], wi_[t]}, (f32x2){0.f, 0.f});
;             float sr = s2.x, si = s2.y;
;             sr += __shfl_xor(sr, 16); si += __shfl_xor(si, 16); sr += __shfl_xor(sr, 32); si += __shfl_xor(si, 32);
;             if (fq == 0) { e[16 * t + fr] = Rr[t]; e[64 + 16 * t + fr] = Ri[t]; }
;             const float nr = fmaf(a64r[t], Rr[t], fmaf(-a64i[t], Ri[t], sr)), ni = fmaf(a64r[t], Ri[t], fmaf(a64i[t], Rr[t], si)); Rr[t] = nr; Ri[t] = ni;
;         }
.LBB0_674:
	global_store_dword v[116:117], v240, off offset:-256
	global_store_dword v[116:117], v241, off
	s_waitcnt vmcnt(9)
	v_mfma_f32_16x16x16_bf16 v[136:139], v[108:109], v[26:27], 0
	v_mfma_f32_16x16x16_bf16 v[140:143], v[108:109], v[28:29], 0
	s_waitcnt vmcnt(8)
	v_mfma_f32_16x16x16_bf16 v[136:139], v[112:113], v[30:31], v[136:139]
	v_mfma_f32_16x16x16_bf16 v[140:143], v[112:113], v[32:33], v[140:143]
	s_waitcnt vmcnt(7)
	v_mfma_f32_16x16x16_bf16 v[136:139], v[114:115], v[34:35], v[136:139]
	v_mfma_f32_16x16x16_bf16 v[140:143], v[114:115], v[36:37], v[140:143]
	s_waitcnt vmcnt(6)
	v_mfma_f32_16x16x16_bf16 v[136:139], v[110:111], v[38:39], v[136:139]
	v_mfma_f32_16x16x16_bf16 v[140:143], v[110:111], v[40:41], v[140:143]
	v_mfma_f32_16x16x16_bf16 v[196:199], v[108:109], v[48:49], 0
	v_mfma_f32_16x16x16_bf16 v[200:203], v[108:109], v[50:51], 0
	v_mfma_f32_16x16x16_bf16 v[196:199], v[112:113], v[52:53], v[196:199]
	v_mfma_f32_16x16x16_bf16 v[200:203], v[112:113], v[54:55], v[200:203]
	v_mfma_f32_16x16x16_bf16 v[196:199], v[114:115], v[56:57], v[196:199]
	v_mfma_f32_16x16x16_bf16 v[200:203], v[114:115], v[58:59], v[200:203]
	v_mfma_f32_16x16x16_bf16 v[196:199], v[110:111], v[60:61], v[196:199]
	v_mfma_f32_16x16x16_bf16 v[200:203], v[110:111], v[62:63], v[200:203]
	v_mfma_f32_16x16x16_bf16 v[208:211], v[108:109], v[70:71], 0
	v_mfma_f32_16x16x16_bf16 v[212:215], v[108:109], v[72:73], 0
	v_mfma_f32_16x16x16_bf16 v[208:211], v[112:113], v[74:75], v[208:211]
	v_mfma_f32_16x16x16_bf16 v[212:215], v[112:113], v[76:77], v[212:215]
	v_mfma_f32_16x16x16_bf16 v[224:227], v[108:109], v[88:89], 0
	v_mfma_f32_16x16x16_bf16 v[228:231], v[108:109], v[90:91], 0
	v_mfma_f32_16x16x16_bf16 v[224:227], v[112:113], v[96:97], v[224:227]
	v_mfma_f32_16x16x16_bf16 v[228:231], v[112:113], v[98:99], v[228:231]
	v_mov_b32_e32 v144, v136
	v_mov_b32_e32 v204, v196
	v_mov_b32_e32 v145, v140
	v_mov_b32_e32 v205, v200
	v_mfma_f32_16x16x16_bf16 v[208:211], v[114:115], v[78:79], v[208:211]
	v_mov_b32_e32 v146, v137
	v_mov_b32_e32 v206, v197
	v_mov_b32_e32 v147, v141
	v_mov_b32_e32 v207, v201
	v_mfma_f32_16x16x16_bf16 v[224:227], v[114:115], v[100:101], v[224:227]
	v_pk_fma_f32 v[144:145], v[18:19], v[144:145], v[146:147]
	v_pk_fma_f32 v[204:205], v[42:43], v[204:205], v[206:207]
	v_mov_b32_e32 v141, v136
	v_mov_b32_e32 v201, v196
	v_mfma_f32_16x16x16_bf16 v[212:215], v[114:115], v[80:81], v[212:215]
	v_pk_fma_f32 v[136:137], v[0:1], v[140:141], v[144:145]
	v_pk_fma_f32 v[196:197], v[4:5], v[200:201], v[204:205]
	v_mov_b32_e32 v140, v138
	v_mov_b32_e32 v200, v198
	v_mfma_f32_16x16x16_bf16 v[188:191], v[114:115], v[102:103], v[228:231]
	v_mov_b32_e32 v141, v142
	v_mov_b32_e32 v201, v202
	v_pk_fma_f32 v[140:141], v[18:19], v[136:137], v[140:141]
	v_pk_fma_f32 v[200:201], v[42:43], v[196:197], v[200:201]
	v_mfma_f32_16x16x16_bf16 v[208:211], v[110:111], v[82:83], v[208:211]
	v_mov_b32_e32 v142, v139
	v_mov_b32_e32 v202, v199
	v_pk_fma_f32 v[136:137], v[0:1], v[136:137], v[140:141] op_sel:[0,1,0] op_sel_hi:[1,0,1]
	v_pk_fma_f32 v[196:197], v[4:5], v[196:197], v[200:201] op_sel:[0,1,0] op_sel_hi:[1,0,1]
	v_mfma_f32_16x16x16_bf16 v[224:227], v[110:111], v[104:105], v[224:227]
	s_nop 0
	s_nop 0
	v_pk_fma_f32 v[138:139], v[18:19], v[136:137], v[142:143]
	v_pk_fma_f32 v[198:199], v[42:43], v[196:197], v[202:203]
	v_mfma_f32_16x16x16_bf16 v[212:215], v[110:111], v[84:85], v[212:215]
	s_nop 0
	s_nop 0
	v_pk_fma_f32 v[136:137], v[0:1], v[136:137], v[138:139] op_sel:[0,1,0] op_sel_hi:[1,0,1]
	v_pk_fma_f32 v[196:197], v[4:5], v[196:197], v[198:199] op_sel:[0,1,0] op_sel_hi:[1,0,1]
	v_mfma_f32_16x16x16_bf16 v[184:187], v[110:111], v[106:107], v[188:191]
	s_nop 0
	s_nop 0
	v_pk_fma_f32 v[138:139], v[22:23], v[136:137], 0 op_sel_hi:[1,1,0]
	v_pk_fma_f32 v[198:199], v[44:45], v[196:197], 0 op_sel_hi:[1,1,0]
	s_nop 0
	s_nop 0
	v_pk_fma_f32 v[136:137], v[24:25], v[136:137], v[138:139] op_sel:[0,1,0] op_sel_hi:[1,0,1]
	v_pk_fma_f32 v[196:197], v[46:47], v[196:197], v[198:199] op_sel:[0,1,0] op_sel_hi:[1,0,1]
	v_mov_b32_e32 v216, v208
	v_mov_b32_e32 v228, v224
	v_mov_b32_e32 v217, v212
	v_mov_b32_e32 v229, v184
	v_mov_b32_e32 v218, v209
	v_mov_b32_e32 v188, v225
	v_mov_b32_e32 v219, v213
	v_mov_b32_e32 v189, v185
	v_pk_fma_f32 v[216:217], v[64:65], v[216:217], v[218:219]
	v_pk_fma_f32 v[188:189], v[86:87], v[228:229], v[188:189]
	v_mov_b32_e32 v213, v208
	v_mov_b32_e32 v185, v224
	v_pk_fma_f32 v[208:209], v[8:9], v[212:213], v[216:217]
	v_pk_fma_f32 v[184:185], v[12:13], v[184:185], v[188:189]
	v_mov_b32_e32 v212, v210
	v_mov_b32_e32 v188, v226
	v_mov_b32_e32 v213, v214
	v_mov_b32_e32 v189, v186
	v_pk_fma_f32 v[212:213], v[64:65], v[208:209], v[212:213]
	v_pk_fma_f32 v[188:189], v[86:87], v[184:185], v[188:189]
	v_mov_b32_e32 v214, v211
	v_mov_b32_e32 v186, v227
	v_pk_fma_f32 v[208:209], v[8:9], v[208:209], v[212:213] op_sel:[0,1,0] op_sel_hi:[1,0,1]
	v_pk_fma_f32 v[184:185], v[12:13], v[184:185], v[188:189] op_sel:[0,1,0] op_sel_hi:[1,0,1]
	s_nop 0
	s_nop 0
	v_pk_fma_f32 v[210:211], v[64:65], v[208:209], v[214:215]
	v_pk_fma_f32 v[186:187], v[86:87], v[184:185], v[186:187]
	s_nop 0
	s_nop 0
	v_pk_fma_f32 v[208:209], v[8:9], v[208:209], v[210:211] op_sel:[0,1,0] op_sel_hi:[1,0,1]
	v_pk_fma_f32 v[184:185], v[12:13], v[184:185], v[186:187] op_sel:[0,1,0] op_sel_hi:[1,0,1]
	s_nop 0
	s_nop 0
	v_pk_fma_f32 v[210:211], v[66:67], v[208:209], 0 op_sel_hi:[1,1,0]
	v_pk_fma_f32 v[186:187], v[92:93], v[184:185], 0 op_sel_hi:[1,1,0]
	s_nop 0
	s_nop 0
	v_pk_fma_f32 v[208:209], v[68:69], v[208:209], v[210:211] op_sel:[0,1,0] op_sel_hi:[1,0,1]
	v_pk_fma_f32 v[184:185], v[94:95], v[184:185], v[186:187] op_sel:[0,1,0] op_sel_hi:[1,0,1]
	s_nop 1
	v_permlane32_swap_b32_e32 v136, v208
	v_permlane32_swap_b32_e32 v137, v209
	v_permlane32_swap_b32_e32 v196, v184
	v_permlane32_swap_b32_e32 v197, v185
	v_add_f32_e32 v136, v136, v208
	v_add_f32_e32 v196, v196, v184
	v_add_f32_e32 v137, v137, v209
	v_add_f32_e32 v197, v197, v185
	s_nop 0
	v_permlane16_swap_b32_e32 v136, v196
	v_permlane16_swap_b32_e32 v137, v197
	v_add_f32_e32 v136, v136, v196
	v_add_f32_e32 v137, v137, v197
	v_fma_f32 v244, -v243, v241, v136
	v_fma_f32 v245, v243, v240, v137
	v_fma_f32 v240, v242, v240, v244
	v_fma_f32 v241, v242, v241, v245
	v_lshl_add_u64 v[116:117], v[116:117], 0, s[4:5]
	v_add_u32_e32 v20, 64, v20
	s_and_b64 vcc, exec, s[22:23]
	s_cbranch_vccnz .LBB0_702
	s_mov_b32 s24, s40
	s_waitcnt vmcnt(3)
	v_mov_b32_e32 v108, v118
	v_mov_b32_e32 v109, v119
	s_waitcnt vmcnt(2)
	v_mov_b32_e32 v112, v120
	v_mov_b32_e32 v113, v121
	s_waitcnt vmcnt(1)
	v_mov_b32_e32 v114, v122
	v_mov_b32_e32 v115, v123
	s_waitcnt vmcnt(0)
	v_mov_b32_e32 v110, v124
	v_mov_b32_e32 v111, v125
	s_branch .LBB0_671
